# v106 + 64-byte alignment of the two mask-free attention bodies
# baseline (speedup 1.0000x reference)
.LBB0_116:
	s_add_i32 s97, s97, 64
	s_cmp_eq_u32 s99, s6
	s_waitcnt lgkmcnt(0)
	s_barrier
	s_cbranch_scc1 .LBB0_120
	s_mov_b32 s42, s6
	s_branch .LBB0_107
	.p2align 6

.Lqt_pf_1:
	s_add_i32 s10, s42, 2
	s_mov_b32 s11, 0
	s_lshl_b64 s[4:5], s[10:11], 13
	s_add_u32 s4, s50, s4
	s_addc_u32 s5, s51, s5
	s_lshl_b64 s[8:9], s[10:11], 14
	s_add_u32 s8, s52, s8
	v_lshl_add_u64 v[252:253], s[4:5], 0, v[176:177]
	s_addc_u32 s9, s53, s9
	global_load_dwordx4 v[160:163], v[252:253], off
	v_add_co_u32_e32 v252, vcc, 0x100000, v252
	v_lshl_add_u64 v[254:255], s[8:9], 0, v[176:177]
	s_nop 0
	v_addc_co_u32_e32 v253, vcc, 0, v253, vcc
	global_load_dwordx4 v[168:171], v[252:253], off
	v_add_co_u32_e32 v252, vcc, 0x2000, v254
	global_load_dwordx4 v[164:167], v[254:255], off
	s_nop 0
	v_addc_co_u32_e32 v253, vcc, 0, v255, vcc
	global_load_dwordx4 v[172:175], v[252:253], off
	v_mfma_f32_32x32x16_bf16 v[128:143], v[216:219], v[200:203], v[128:143]
	v_mfma_f32_32x32x16_bf16 v[96:111], v[224:227], v[200:203], v[96:111]
	v_mfma_f32_32x32x16_bf16 v[64:79], v[232:235], v[200:203], v[64:79]
	v_mfma_f32_32x32x16_bf16 v[32:47], v[244:247], v[200:203], v[32:47]
	v_mfma_f32_32x32x16_bf16 v[128:143], v[220:223], v[204:207], v[128:143]
	v_mfma_f32_32x32x16_bf16 v[96:111], v[228:231], v[204:207], v[96:111]
	v_mfma_f32_32x32x16_bf16 v[64:79], v[236:239], v[204:207], v[64:79]
	v_mfma_f32_32x32x16_bf16 v[32:47], v[248:251], v[204:207], v[32:47]
	s_branch .LBB0_116
	.p2align 6
